# stack3: stack2 + top-k radix select specialized by number of candidate key words (skips compares on all-zero key vectors)
# speedup vs baseline: 1.0208x; 1.0130x over previous
; __device__ __forceinline__ void nsa_unit(int hk, int T, LAS unsigned char* lds, LAS float* wsf, const AttnPtrs& P) {
;     ...
;                 unsigned k0 = 0u, k1 = 0u, k2 = 0u, k3 = 0u;
;                 { int j = lane; if (j >= 1 && j <= T - 2) k0 = __float_as_uint(irow[j]) + 1u; j += 64; if (j <= T - 2) k1 = __float_as_uint(irow[j]) + 1u;
;                   j += 64; if (j <= T - 2) k2 = __float_as_uint(irow[j]) + 1u; j += 64; if (j <= T - 2) k3 = __float_as_uint(irow[j]) + 1u; }
;                 unsigned prefix = 0u;
;     ...
;                     const unsigned cand = prefix | (1u << bit);
;                     const int cnt = __popcll(__ballot(k0 >= cand)) + __popcll(__ballot(k1 >= cand)) + __popcll(__ballot(k2 >= cand)) + __popcll(__ballot(k3 >= cand));
;                     if (cnt >= npick) prefix = cand;
;                 }
.LBB0_1440:
	s_or_b64 exec, exec, s[20:21]
	s_mov_b32 s20, 31
	s_mov_b32 s34, 0
	s_cmp_lt_u32 s97, 66
	s_cbranch_scc1 .Ltk1
	s_cmp_lt_u32 s97, 130
	s_cbranch_scc1 .Ltk2
	s_cmp_lt_u32 s97, 194
	s_cbranch_scc1 .Ltk3
.LBB0_1441:
	s_lshl_b32 s21, 1, s20
	s_or_b32 s21, s21, s34
	v_cmp_le_u32_e32 vcc, s21, v7
	s_bcnt1_i32_b64 s22, vcc
	v_cmp_le_u32_e32 vcc, s21, v6
	s_bcnt1_i32_b64 s23, vcc
	s_add_i32 s22, s22, s23
	v_cmp_le_u32_e32 vcc, s21, v14
	s_bcnt1_i32_b64 s23, vcc
	s_add_i32 s22, s22, s23
	v_cmp_le_u32_e32 vcc, s21, v13
	s_bcnt1_i32_b64 s23, vcc
	s_add_i32 s22, s22, s23
	s_cmp_lt_u32 s22, s46
	s_cselect_b32 s21, s34, s21
	s_add_i32 s22, s20, -1
	s_lshl_b32 s22, 1, s22
	s_or_b32 s22, s22, s21
	v_cmp_le_u32_e32 vcc, s22, v7
	s_bcnt1_i32_b64 s23, vcc
	v_cmp_le_u32_e32 vcc, s22, v6
	s_bcnt1_i32_b64 s24, vcc
	s_add_i32 s23, s23, s24
	v_cmp_le_u32_e32 vcc, s22, v14
	s_bcnt1_i32_b64 s24, vcc
	s_add_i32 s23, s23, s24
	v_cmp_le_u32_e32 vcc, s22, v13
	s_bcnt1_i32_b64 s24, vcc
	s_add_i32 s23, s23, s24
	s_cmp_lt_u32 s23, s46
	s_cselect_b32 s21, s21, s22
	s_add_i32 s22, s20, -2
	s_lshl_b32 s22, 1, s22
	s_or_b32 s22, s22, s21
	v_cmp_le_u32_e32 vcc, s22, v7
	s_bcnt1_i32_b64 s23, vcc
	v_cmp_le_u32_e32 vcc, s22, v6
	s_bcnt1_i32_b64 s24, vcc
	s_add_i32 s23, s23, s24
	v_cmp_le_u32_e32 vcc, s22, v14
	s_bcnt1_i32_b64 s24, vcc
	s_add_i32 s23, s23, s24
	v_cmp_le_u32_e32 vcc, s22, v13
	s_bcnt1_i32_b64 s24, vcc
	s_add_i32 s23, s23, s24
	s_cmp_lt_u32 s23, s46
	s_cselect_b32 s21, s21, s22
	s_add_i32 s20, s20, -3
	s_lshl_b32 s22, 1, s20
	s_or_b32 s22, s22, s21
	v_cmp_le_u32_e32 vcc, s22, v7
	s_bcnt1_i32_b64 s23, vcc
	v_cmp_le_u32_e32 vcc, s22, v6
	s_bcnt1_i32_b64 s24, vcc
	s_add_i32 s23, s23, s24
	v_cmp_le_u32_e32 vcc, s22, v14
	s_bcnt1_i32_b64 s24, vcc
	s_add_i32 s23, s23, s24
	v_cmp_le_u32_e32 vcc, s22, v13
	s_bcnt1_i32_b64 s24, vcc
	s_add_i32 s23, s23, s24
	s_cmp_lt_u32 s23, s46
	s_cselect_b32 s34, s21, s22
	s_sub_u32 s20, s20, 1
	s_cbranch_scc0 .LBB0_1441
	s_branch .Ltk_done
.Ltk1:
	s_lshl_b32 s21, 1, s20
	s_or_b32 s21, s21, s34
	v_cmp_le_u32_e32 vcc, s21, v7
	s_bcnt1_i32_b64 s22, vcc
	s_cmp_lt_u32 s22, s46
	s_cselect_b32 s21, s34, s21
	s_add_i32 s22, s20, -1
	s_lshl_b32 s22, 1, s22
	s_or_b32 s22, s22, s21
	v_cmp_le_u32_e32 vcc, s22, v7
	s_bcnt1_i32_b64 s23, vcc
	s_cmp_lt_u32 s23, s46
	s_cselect_b32 s21, s21, s22
	s_add_i32 s22, s20, -2
	s_lshl_b32 s22, 1, s22
	s_or_b32 s22, s22, s21
	v_cmp_le_u32_e32 vcc, s22, v7
	s_bcnt1_i32_b64 s23, vcc
	s_cmp_lt_u32 s23, s46
	s_cselect_b32 s21, s21, s22
	s_add_i32 s20, s20, -3
	s_lshl_b32 s22, 1, s20
	s_or_b32 s22, s22, s21
	v_cmp_le_u32_e32 vcc, s22, v7
	s_bcnt1_i32_b64 s23, vcc
	s_cmp_lt_u32 s23, s46
	s_cselect_b32 s34, s21, s22
	s_sub_u32 s20, s20, 1
	s_cbranch_scc0 .Ltk1
	s_branch .Ltk_done
.Ltk2:
	s_lshl_b32 s21, 1, s20
	s_or_b32 s21, s21, s34
	v_cmp_le_u32_e32 vcc, s21, v7
	s_bcnt1_i32_b64 s22, vcc
	v_cmp_le_u32_e32 vcc, s21, v6
	s_bcnt1_i32_b64 s23, vcc
	s_add_i32 s22, s22, s23
	s_cmp_lt_u32 s22, s46
	s_cselect_b32 s21, s34, s21
	s_add_i32 s22, s20, -1
	s_lshl_b32 s22, 1, s22
	s_or_b32 s22, s22, s21
	v_cmp_le_u32_e32 vcc, s22, v7
	s_bcnt1_i32_b64 s23, vcc
	v_cmp_le_u32_e32 vcc, s22, v6
	s_bcnt1_i32_b64 s24, vcc
	s_add_i32 s23, s23, s24
	s_cmp_lt_u32 s23, s46
	s_cselect_b32 s21, s21, s22
	s_add_i32 s22, s20, -2
	s_lshl_b32 s22, 1, s22
	s_or_b32 s22, s22, s21
	v_cmp_le_u32_e32 vcc, s22, v7
	s_bcnt1_i32_b64 s23, vcc
	v_cmp_le_u32_e32 vcc, s22, v6
	s_bcnt1_i32_b64 s24, vcc
	s_add_i32 s23, s23, s24
	s_cmp_lt_u32 s23, s46
	s_cselect_b32 s21, s21, s22
	s_add_i32 s20, s20, -3
	s_lshl_b32 s22, 1, s20
	s_or_b32 s22, s22, s21
	v_cmp_le_u32_e32 vcc, s22, v7
	s_bcnt1_i32_b64 s23, vcc
	v_cmp_le_u32_e32 vcc, s22, v6
	s_bcnt1_i32_b64 s24, vcc
	s_add_i32 s23, s23, s24
	s_cmp_lt_u32 s23, s46
	s_cselect_b32 s34, s21, s22
	s_sub_u32 s20, s20, 1
	s_cbranch_scc0 .Ltk2
	s_branch .Ltk_done
; __device__ __forceinline__ void nsa_unit(int hk, int T, LAS unsigned char* lds, LAS float* wsf, const AttnPtrs& P) {
;     ...
;                     const unsigned cand = prefix | (1u << bit);
;                     const int cnt = __popcll(__ballot(k0 >= cand)) + __popcll(__ballot(k1 >= cand)) + __popcll(__ballot(k2 >= cand)) + __popcll(__ballot(k3 >= cand));
;                     if (cnt >= npick) prefix = cand;
;                 }
;                 const unsigned long long g0 = __ballot(k0 > prefix), g1 = __ballot(k1 > prefix), g2 = __ballot(k2 > prefix), g3 = __ballot(k3 > prefix);
;                 const unsigned long long e0 = __ballot(k0 == prefix), e1 = __ballot(k1 == prefix), e2 = __ballot(k2 == prefix), e3 = __ballot(k3 == prefix);
;                 const int need = npick - (__popcll(g0) + __popcll(g1) + __popcll(g2) + __popcll(g3));
;                 const unsigned long long ltm = (lane == 0) ? 0ull : ((~0ull) >> (64 - lane));
;                 int base = 0;
;                 const bool c0 = ((e0 >> lane) & 1ull) && (base + __popcll(e0 & ltm) < need); base += __popcll(e0);
;                 const bool c1 = ((e1 >> lane) & 1ull) && (base + __popcll(e1 & ltm) < need); base += __popcll(e1);
;                 const bool c2 = ((e2 >> lane) & 1ull) && (base + __popcll(e2 & ltm) < need); base += __popcll(e2);
;                 const bool c3 = ((e3 >> lane) & 1ull) && (base + __popcll(e3 & ltm) < need);
;                 const unsigned long long s0 = g0 | __ballot(c0), s1 = g1 | __ballot(c1), s2 = g2 | __ballot(c2), s3 = g3 | __ballot(c3);
;                 const unsigned long long sm = (lane >> 1) == 0 ? s0 : (lane >> 1) == 1 ? s1 : (lane >> 1) == 2 ? s2 : s3;
;                 if (lane < 8) myword |= (lane & 1) ? (unsigned)(sm >> 32) : (unsigned)sm;
.Ltk3:
	s_lshl_b32 s21, 1, s20
	s_or_b32 s21, s21, s34
	v_cmp_le_u32_e32 vcc, s21, v7
	s_bcnt1_i32_b64 s22, vcc
	v_cmp_le_u32_e32 vcc, s21, v6
	s_bcnt1_i32_b64 s23, vcc
	s_add_i32 s22, s22, s23
	v_cmp_le_u32_e32 vcc, s21, v14
	s_bcnt1_i32_b64 s23, vcc
	s_add_i32 s22, s22, s23
	s_cmp_lt_u32 s22, s46
	s_cselect_b32 s21, s34, s21
	s_add_i32 s22, s20, -1
	s_lshl_b32 s22, 1, s22
	s_or_b32 s22, s22, s21
	v_cmp_le_u32_e32 vcc, s22, v7
	s_bcnt1_i32_b64 s23, vcc
	v_cmp_le_u32_e32 vcc, s22, v6
	s_bcnt1_i32_b64 s24, vcc
	s_add_i32 s23, s23, s24
	v_cmp_le_u32_e32 vcc, s22, v14
	s_bcnt1_i32_b64 s24, vcc
	s_add_i32 s23, s23, s24
	s_cmp_lt_u32 s23, s46
	s_cselect_b32 s21, s21, s22
	s_add_i32 s22, s20, -2
	s_lshl_b32 s22, 1, s22
	s_or_b32 s22, s22, s21
	v_cmp_le_u32_e32 vcc, s22, v7
	s_bcnt1_i32_b64 s23, vcc
	v_cmp_le_u32_e32 vcc, s22, v6
	s_bcnt1_i32_b64 s24, vcc
	s_add_i32 s23, s23, s24
	v_cmp_le_u32_e32 vcc, s22, v14
	s_bcnt1_i32_b64 s24, vcc
	s_add_i32 s23, s23, s24
	s_cmp_lt_u32 s23, s46
	s_cselect_b32 s21, s21, s22
	s_add_i32 s20, s20, -3
	s_lshl_b32 s22, 1, s20
	s_or_b32 s22, s22, s21
	v_cmp_le_u32_e32 vcc, s22, v7
	s_bcnt1_i32_b64 s23, vcc
	v_cmp_le_u32_e32 vcc, s22, v6
	s_bcnt1_i32_b64 s24, vcc
	s_add_i32 s23, s23, s24
	v_cmp_le_u32_e32 vcc, s22, v14
	s_bcnt1_i32_b64 s24, vcc
	s_add_i32 s23, s23, s24
	s_cmp_lt_u32 s23, s46
	s_cselect_b32 s34, s21, s22
	s_sub_u32 s20, s20, 1
	s_cbranch_scc0 .Ltk3
.Ltk_done:
	v_cmp_lt_u32_e32 vcc, s34, v7
	v_cmp_lt_u32_e64 s[20:21], s34, v6
	v_cmp_lt_u32_e64 s[22:23], s34, v14
	s_bcnt1_i32_b64 s36, vcc
	s_bcnt1_i32_b64 s37, s[20:21]
	v_cmp_lt_u32_e64 s[24:25], s34, v13
	s_bcnt1_i32_b64 s38, s[22:23]
	s_add_i32 s36, s36, s37
	v_cmp_eq_u32_e64 s[26:27], s34, v7
	s_bcnt1_i32_b64 s39, s[24:25]
	s_add_i32 s36, s36, s38
	v_cmp_eq_u32_e64 s[28:29], s34, v6
	s_add_i32 s36, s36, s39
	v_and_b32_e32 v7, s27, v5
	v_and_b32_e32 v6, s26, v4
	s_sub_i32 s50, s46, s36
	v_cmp_ne_u64_e64 s[36:37], 0, v[6:7]
	v_and_b32_e32 v7, s26, v0
	v_and_b32_e32 v6, s27, v3
	v_bcnt_u32_b32 v7, v7, 0
	v_bcnt_u32_b32 v6, v6, v7
	v_cmp_gt_u32_e64 s[38:39], s50, v6
	v_and_b32_e32 v7, s29, v5
	v_and_b32_e32 v6, s28, v4
	s_bcnt1_i32_b64 s51, s[26:27]
	v_cmp_ne_u64_e64 s[26:27], 0, v[6:7]
	v_and_b32_e32 v7, s28, v0
	v_and_b32_e32 v6, s29, v3
	v_bcnt_u32_b32 v7, v7, 0
	v_bcnt_u32_b32 v6, v6, v7
	v_add_u32_e32 v6, s51, v6
	v_cmp_eq_u32_e64 s[30:31], s34, v14
	s_and_b64 s[38:39], s[36:37], s[38:39]
	v_cmp_gt_u32_e64 s[36:37], s50, v6
	s_and_b64 s[36:37], s[26:27], s[36:37]
	s_bcnt1_i32_b64 s26, s[28:29]
	v_and_b32_e32 v7, s31, v5
	v_and_b32_e32 v6, s30, v4
	s_add_i32 s51, s26, s51
	v_cmp_ne_u64_e64 s[26:27], 0, v[6:7]
	v_and_b32_e32 v7, s30, v0
	v_and_b32_e32 v6, s31, v3
	v_bcnt_u32_b32 v7, v7, 0
	v_bcnt_u32_b32 v6, v6, v7
	v_cmp_eq_u32_e64 s[34:35], s34, v13
	v_add_u32_e32 v6, s51, v6
	v_cmp_gt_u32_e64 s[28:29], s50, v6
	v_and_b32_e32 v7, s35, v5
	v_and_b32_e32 v6, s34, v4
	s_and_b64 s[66:67], s[26:27], s[28:29]
	v_cmp_ne_u64_e64 s[26:27], 0, v[6:7]
	v_and_b32_e32 v7, s34, v0
	s_bcnt1_i32_b64 s28, s[30:31]
	v_and_b32_e32 v6, s35, v3
	v_bcnt_u32_b32 v7, v7, 0
	s_add_i32 s51, s51, s28
	v_bcnt_u32_b32 v6, v6, v7
	v_add_u32_e32 v6, s51, v6
	v_cmp_gt_u32_e64 s[28:29], s50, v6
	v_cndmask_b32_e64 v6, 0, 1, s[38:39]
	s_and_b64 s[34:35], s[26:27], s[28:29]
	v_cmp_ne_u32_e64 s[26:27], 0, v6
	v_cndmask_b32_e64 v6, 0, 1, s[36:37]
	v_cmp_ne_u32_e64 s[28:29], 0, v6
	v_cndmask_b32_e64 v6, 0, 1, s[66:67]
	v_cmp_ne_u32_e64 s[30:31], 0, v6
	v_cndmask_b32_e64 v6, 0, 1, s[34:35]
	v_cmp_ne_u32_e64 s[34:35], 0, v6
	s_and_saveexec_b64 s[36:37], s[12:13]
	s_xor_b64 s[36:37], exec, s[36:37]
	s_cbranch_execz .LBB0_1444
	s_or_b64 s[24:25], s[34:35], s[24:25]
	s_or_b64 s[22:23], s[30:31], s[22:23]
	v_mov_b32_e32 v6, s24
	v_mov_b32_e32 v7, s22
	s_or_b64 s[20:21], s[28:29], s[20:21]
	v_cndmask_b32_e64 v6, v6, v7, s[16:17]
	v_mov_b32_e32 v7, s25
	v_mov_b32_e32 v13, s23
	v_cndmask_b32_e64 v7, v7, v13, s[16:17]
	v_mov_b32_e32 v13, s21
	v_cndmask_b32_e64 v7, v7, v13, s[14:15]
	v_mov_b32_e32 v13, s20
	v_cndmask_b32_e64 v6, v6, v13, s[14:15]
